# v28 + nt hint on the q|k|v/gate in-projection epilogue's sigmoid-gate stores (consumed only from phase 4 on)
# speedup vs baseline: 1.0017x; 1.0017x over previous
; __device__ __forceinline__ unsigned pk_bf16(float lo, float hi) { const f32x2 v = {lo, hi}; return __builtin_bit_cast(unsigned, __builtin_convertvector(v, b16x2)); }
; __device__ __forceinline__ float sigmoidf_(float x) { return __builtin_amdgcn_rcpf(1.0f + __expf(-x)); }
;     __device__ __forceinline__ void row(int r, int col32, int fq, const f32x4& a00, const f32x4& a01, const f32x4& a10, const f32x4& a11) const { half(r, col32, fq, a00, a01); half(r, col32 + HALF, fq, a10, a11); }
;     __device__ __forceinline__ void row(int r, int col32, int fq, const f32x4& a00, const f32x4& a01, const f32x4& a10, const f32x4& a11) const { half(r, col32, fq, a00, a01); half(r, col32 + HALF, fq, a10, a11); }
;     __device__ __forceinline__ void row(int r, int col32, int fq, const f32x4& a00, const f32x4& a01, const f32x4& a10, const f32x4& a11) const { half(r, col32, fq, a00, a01); half(r, col32 + HALF, fq, a10, a11); }
;     __device__ __forceinline__ void half(int row, int col32, int fq, const f32x4& v0, const f32x4& v1) const {
;         if constexpr (PERM_) {
;             const int col = col32 + 8 * fq, b = row / TP, t = row - b * TP;
;             if (col < 1536) {
;                 const int which = col >> 9, hc = col & 511, h = hc >> 6, d = hc & 63;
;                 const float s = which == 0 ? 0.125f : 1.0f;
;                 u32x4 w; w.x = pk_bf16(v0[0] * s, v0[1] * s); w.y = pk_bf16(v0[2] * s, v0[3] * s); w.z = pk_bf16(v1[0] * s, v1[1] * s); w.w = pk_bf16(v1[2] * s, v1[3] * s);
;                 *(u32x4*)(qkv + (size_t)which * (QKV_ONE / 2) + ((size_t)(b * NH + h) * TP + t) * 64 + d) = w;
;             } else if (t >= NMETA && t < T) {
;                 u32x4 w; w.x = pk_bf16(sigmoidf_(v0[0]), sigmoidf_(v0[1])); w.y = pk_bf16(sigmoidf_(v0[2]), sigmoidf_(v0[3]));
;                 w.z = pk_bf16(sigmoidf_(v1[0]), sigmoidf_(v1[1])); w.w = pk_bf16(sigmoidf_(v1[2]), sigmoidf_(v1[3]));
;                 *(u32x4*)(gates + (size_t)(b * SEQ + t - NMETA) * 2048 + (col - 3328)) = w;
;             }
.LBB0_649:
	v_lshl_add_u32 v184, s0, 8, v177
	s_lshl_b32 s1, s6, 8
	v_mul_hi_i32 v150, v184, s60
	s_or_b32 s21, s1, s41
	s_ashr_i32 s6, s6, 1
	v_lshrrev_b32_e32 v151, 31, v150
	v_ashrrev_i32_e32 v150, 12, v150
	s_cmpk_lt_u32 s1, 0x200
	s_mul_hi_i32 s7, s6, 0x2080000
	s_mul_i32 s6, s6, 0x2080000
	v_add_u32_e32 v185, v150, v151
	v_or_b32_e32 v138, s21, v178
	s_cselect_b64 s[0:1], -1, 0
	s_add_u32 s6, s50, s6
	v_mad_i32_i24 v154, v185, s61, v184
	v_cmp_lt_i32_e64 s[4:5], s55, v138
	v_lshl_add_u64 v[148:149], v[138:139], 1, s[88:89]
	s_addc_u32 s7, s51, s7
	v_add_u32_e32 v186, -16, v154
	s_and_saveexec_b64 s[26:27], s[4:5]
	s_xor_b64 s[26:27], exec, s[26:27]
	s_cbranch_execz .LBB0_653
	v_cmp_gt_u32_e32 vcc, s40, v186
	s_and_saveexec_b64 s[28:29], vcc
	s_cbranch_execz .LBB0_652
	v_mul_f32_e32 v150, 0xbfb8aa3b, v124
	v_mul_f32_e32 v151, 0xbfb8aa3b, v125
	v_exp_f32_e32 v150, v150
	v_exp_f32_e32 v151, v151
	v_mul_f32_e32 v188, 0xbfb8aa3b, v121
	v_exp_f32_e32 v188, v188
	v_mul_f32_e32 v189, 0xbfb8aa3b, v122
	v_exp_f32_e32 v189, v189
	v_mul_f32_e32 v190, 0xbfb8aa3b, v123
	v_add_f32_e32 v150, 1.0, v150
	v_add_f32_e32 v151, 1.0, v151
	v_mul_f32_e32 v152, 0xbfb8aa3b, v126
	v_mul_f32_e32 v155, 0xbfb8aa3b, v127
	v_mul_f32_e32 v187, 0xbfb8aa3b, v120
	v_exp_f32_e32 v190, v190
	v_rcp_f32_e32 v150, v150
	v_exp_f32_e32 v152, v152
	v_exp_f32_e32 v155, v155
	v_rcp_f32_e32 v151, v151
	v_exp_f32_e32 v187, v187
	v_add_f32_e32 v188, 1.0, v188
	v_rcp_f32_e32 v191, v188
	v_add_f32_e32 v188, 1.0, v189
	v_rcp_f32_e32 v192, v188
	v_add_f32_e32 v188, 1.0, v190
	v_add_f32_e32 v152, 1.0, v152
	v_add_f32_e32 v155, 1.0, v155
	v_add_f32_e32 v187, 1.0, v187
	v_rcp_f32_e32 v193, v188
	v_cvt_pk_bf16_f32 v188, v150, v151
	v_lshl_add_u32 v150, v185, 13, v186
	v_rcp_f32_e32 v152, v152
	v_rcp_f32_e32 v155, v155
	v_rcp_f32_e32 v187, v187
	v_ashrrev_i32_e32 v151, 31, v150
	v_lshlrev_b64 v[150:151], 12, v[150:151]
	v_lshl_add_u64 v[150:151], v[148:149], 0, v[150:151]
	v_add_co_u32_e32 v150, vcc, 0xfffff000, v150
	v_cvt_pk_bf16_f32 v189, v152, v155
	v_cvt_pk_bf16_f32 v190, v187, v191
	v_cvt_pk_bf16_f32 v191, v192, v193
	v_addc_co_u32_e32 v151, vcc, -1, v151, vcc
	global_store_dwordx4 v[150:151], v[188:191], off offset:-2560 nt

; __device__ __forceinline__ unsigned pk_bf16(float lo, float hi) { const f32x2 v = {lo, hi}; return __builtin_bit_cast(unsigned, __builtin_convertvector(v, b16x2)); }
; __device__ __forceinline__ float sigmoidf_(float x) { return __builtin_amdgcn_rcpf(1.0f + __expf(-x)); }
;     __device__ __forceinline__ void half(int row, int col32, int fq, const f32x4& v0, const f32x4& v1) const {
;     ...
;                 u32x4 w; w.x = pk_bf16(v0[0] * s, v0[1] * s); w.y = pk_bf16(v0[2] * s, v0[3] * s); w.z = pk_bf16(v1[0] * s, v1[1] * s); w.w = pk_bf16(v1[2] * s, v1[3] * s);
;                 *(u32x4*)(qkv + (size_t)which * (QKV_ONE / 2) + ((size_t)(b * NH + h) * TP + t) * 64 + d) = w;
;             } else if (t >= NMETA && t < T) {
;                 u32x4 w; w.x = pk_bf16(sigmoidf_(v0[0]), sigmoidf_(v0[1])); w.y = pk_bf16(sigmoidf_(v0[2]), sigmoidf_(v0[3]));
;                 w.z = pk_bf16(sigmoidf_(v1[0]), sigmoidf_(v1[1])); w.w = pk_bf16(sigmoidf_(v1[2]), sigmoidf_(v1[3]));
;                 *(u32x4*)(gates + (size_t)(b * SEQ + t - NMETA) * 2048 + (col - 3328)) = w;
.LBB0_655:
	s_or_b64 exec, exec, s[26:27]
	v_or_b32_e32 v120, 0x80, v138
	v_cmp_lt_i32_e64 s[6:7], s55, v120
	s_and_saveexec_b64 s[0:1], s[6:7]
	s_xor_b64 s[0:1], exec, s[0:1]
	s_cbranch_execz .LBB0_659
	v_cmp_gt_u32_e32 vcc, s40, v186
	s_and_saveexec_b64 s[26:27], vcc
	s_cbranch_execz .LBB0_658
	v_mul_f32_e32 v123, 0xbfb8aa3b, v118
	v_mul_f32_e32 v124, 0xbfb8aa3b, v119
	v_mul_f32_e32 v125, 0xbfb8aa3b, v112
	v_mul_f32_e32 v126, 0xbfb8aa3b, v113
	v_exp_f32_e32 v123, v123
	v_exp_f32_e32 v124, v124
	v_exp_f32_e32 v125, v125
	v_exp_f32_e32 v126, v126
	v_mul_f32_e32 v127, 0xbfb8aa3b, v114
	v_mul_f32_e32 v138, 0xbfb8aa3b, v115
	v_exp_f32_e32 v127, v127
	v_exp_f32_e32 v138, v138
	v_mul_f32_e32 v121, 0xbfb8aa3b, v116
	v_mul_f32_e32 v122, 0xbfb8aa3b, v117
	v_add_f32_e32 v123, 1.0, v123
	v_add_f32_e32 v124, 1.0, v124
	v_add_f32_e32 v125, 1.0, v125
	v_add_f32_e32 v126, 1.0, v126
	v_exp_f32_e32 v121, v121
	v_exp_f32_e32 v122, v122
	v_rcp_f32_e32 v123, v123
	v_rcp_f32_e32 v124, v124
	v_rcp_f32_e32 v125, v125
	v_rcp_f32_e32 v126, v126
	v_add_f32_e32 v127, 1.0, v127
	v_add_f32_e32 v138, 1.0, v138
	v_rcp_f32_e32 v127, v127
	v_rcp_f32_e32 v138, v138
	v_add_f32_e32 v121, 1.0, v121
	v_add_f32_e32 v122, 1.0, v122
	v_cvt_pk_bf16_f32 v123, v123, v124
	v_cvt_pk_bf16_f32 v124, v125, v126
	v_lshl_add_u32 v126, v185, 13, v186
	v_rcp_f32_e32 v121, v121
	v_rcp_f32_e32 v122, v122
	v_cvt_pk_bf16_f32 v125, v127, v138
	v_ashrrev_i32_e32 v127, 31, v126
	v_lshlrev_b64 v[126:127], 12, v[126:127]
	v_lshl_add_u64 v[126:127], v[148:149], 0, v[126:127]
	v_add_co_u32_e32 v126, vcc, 0xfffff000, v126
	v_cvt_pk_bf16_f32 v122, v121, v122
	s_nop 0
	v_addc_co_u32_e32 v127, vcc, -1, v127, vcc
	global_store_dwordx4 v[126:127], v[122:125], off offset:-2304 nt

; __device__ __forceinline__ unsigned pk_bf16(float lo, float hi) { const f32x2 v = {lo, hi}; return __builtin_bit_cast(unsigned, __builtin_convertvector(v, b16x2)); }
; __device__ __forceinline__ float sigmoidf_(float x) { return __builtin_amdgcn_rcpf(1.0f + __expf(-x)); }
;     __device__ __forceinline__ void row(int r, int col32, int fq, const f32x4& a00, const f32x4& a01, const f32x4& a10, const f32x4& a11) const { half(r, col32, fq, a00, a01); half(r, col32 + HALF, fq, a10, a11); }
;     __device__ __forceinline__ void row(int r, int col32, int fq, const f32x4& a00, const f32x4& a01, const f32x4& a10, const f32x4& a11) const { half(r, col32, fq, a00, a01); half(r, col32 + HALF, fq, a10, a11); }
;     __device__ __forceinline__ void row(int r, int col32, int fq, const f32x4& a00, const f32x4& a01, const f32x4& a10, const f32x4& a11) const { half(r, col32, fq, a00, a01); half(r, col32 + HALF, fq, a10, a11); }
;     __device__ __forceinline__ void half(int row, int col32, int fq, const f32x4& v0, const f32x4& v1) const {
;     ...
;             const int col = col32 + 8 * fq, b = row / TP, t = row - b * TP;
;             if (col < 1536) {
;                 const int which = col >> 9, hc = col & 511, h = hc >> 6, d = hc & 63;
;                 const float s = which == 0 ? 0.125f : 1.0f;
;                 u32x4 w; w.x = pk_bf16(v0[0] * s, v0[1] * s); w.y = pk_bf16(v0[2] * s, v0[3] * s); w.z = pk_bf16(v1[0] * s, v1[1] * s); w.w = pk_bf16(v1[2] * s, v1[3] * s);
;                 *(u32x4*)(qkv + (size_t)which * (QKV_ONE / 2) + ((size_t)(b * NH + h) * TP + t) * 64 + d) = w;
;             } else if (t >= NMETA && t < T) {
;                 u32x4 w; w.x = pk_bf16(sigmoidf_(v0[0]), sigmoidf_(v0[1])); w.y = pk_bf16(sigmoidf_(v0[2]), sigmoidf_(v0[3]));
;                 w.z = pk_bf16(sigmoidf_(v1[0]), sigmoidf_(v1[1])); w.w = pk_bf16(sigmoidf_(v1[2]), sigmoidf_(v1[3]));
;                 *(u32x4*)(gates + (size_t)(b * SEQ + t - NMETA) * 2048 + (col - 3328)) = w;
.LBB0_661:
	s_or_b64 exec, exec, s[0:1]
	v_or_b32_e32 v112, 16, v184
	v_mul_hi_i32 v113, v112, s60
	v_lshrrev_b32_e32 v114, 31, v113
	v_ashrrev_i32_e32 v113, 12, v113
	v_add_u32_e32 v114, v113, v114
	v_mad_i32_i24 v112, v114, s61, v112
	v_add_u32_e32 v115, -16, v112
	s_and_saveexec_b64 s[0:1], s[4:5]
	s_xor_b64 s[0:1], exec, s[0:1]
	s_cbranch_execz .LBB0_669
	v_cmp_gt_u32_e32 vcc, s40, v115
	s_and_saveexec_b64 s[26:27], vcc
	s_cbranch_execz .LBB0_664
	v_mul_f32_e32 v117, 0xbfb8aa3b, v110
	v_mul_f32_e32 v118, 0xbfb8aa3b, v111
	v_mul_f32_e32 v119, 0xbfb8aa3b, v104
	v_mul_f32_e32 v121, 0xbfb8aa3b, v105
	v_mul_f32_e32 v122, 0xbfb8aa3b, v106
	v_mul_f32_e32 v123, 0xbfb8aa3b, v107
	v_exp_f32_e32 v117, v117
	v_exp_f32_e32 v118, v118
	v_exp_f32_e32 v119, v119
	v_exp_f32_e32 v121, v121
	v_exp_f32_e32 v122, v122
	v_exp_f32_e32 v123, v123
	v_mul_f32_e32 v113, 0xbfb8aa3b, v108
	v_mul_f32_e32 v116, 0xbfb8aa3b, v109
	v_add_f32_e32 v117, 1.0, v117
	v_add_f32_e32 v118, 1.0, v118
	v_add_f32_e32 v119, 1.0, v119
	v_add_f32_e32 v121, 1.0, v121
	v_add_f32_e32 v122, 1.0, v122
	v_add_f32_e32 v123, 1.0, v123
	v_exp_f32_e32 v113, v113
	v_exp_f32_e32 v116, v116
	v_rcp_f32_e32 v117, v117
	v_rcp_f32_e32 v118, v118
	v_rcp_f32_e32 v119, v119
	v_rcp_f32_e32 v121, v121
	v_rcp_f32_e32 v122, v122
	v_rcp_f32_e32 v123, v123
	v_add_f32_e32 v113, 1.0, v113
	v_add_f32_e32 v116, 1.0, v116
	v_cvt_pk_bf16_f32 v117, v117, v118
	v_cvt_pk_bf16_f32 v118, v119, v121
	v_cvt_pk_bf16_f32 v119, v122, v123
	v_lshl_add_u32 v122, v114, 13, v115
	v_rcp_f32_e32 v113, v113
	v_rcp_f32_e32 v116, v116
	v_ashrrev_i32_e32 v123, 31, v122
	v_lshlrev_b64 v[122:123], 12, v[122:123]
	v_lshl_add_u64 v[122:123], v[148:149], 0, v[122:123]
	v_add_co_u32_e32 v122, vcc, 0xfffff000, v122
	v_cvt_pk_bf16_f32 v116, v113, v116
	s_nop 0
	v_addc_co_u32_e32 v123, vcc, -1, v123, vcc
	global_store_dwordx4 v[122:123], v[116:119], off offset:-2560 nt

; __device__ __forceinline__ unsigned pk_bf16(float lo, float hi) { const f32x2 v = {lo, hi}; return __builtin_bit_cast(unsigned, __builtin_convertvector(v, b16x2)); }
; __device__ __forceinline__ float sigmoidf_(float x) { return __builtin_amdgcn_rcpf(1.0f + __expf(-x)); }
;     __device__ __forceinline__ void half(int row, int col32, int fq, const f32x4& v0, const f32x4& v1) const {
;     ...
;                 u32x4 w; w.x = pk_bf16(v0[0] * s, v0[1] * s); w.y = pk_bf16(v0[2] * s, v0[3] * s); w.z = pk_bf16(v1[0] * s, v1[1] * s); w.w = pk_bf16(v1[2] * s, v1[3] * s);
;                 *(u32x4*)(qkv + (size_t)which * (QKV_ONE / 2) + ((size_t)(b * NH + h) * TP + t) * 64 + d) = w;
;             } else if (t >= NMETA && t < T) {
;                 u32x4 w; w.x = pk_bf16(sigmoidf_(v0[0]), sigmoidf_(v0[1])); w.y = pk_bf16(sigmoidf_(v0[2]), sigmoidf_(v0[3]));
;                 w.z = pk_bf16(sigmoidf_(v1[0]), sigmoidf_(v1[1])); w.w = pk_bf16(sigmoidf_(v1[2]), sigmoidf_(v1[3]));
;                 *(u32x4*)(gates + (size_t)(b * SEQ + t - NMETA) * 2048 + (col - 3328)) = w;
.LBB0_666:
	v_cmp_gt_u32_e32 vcc, s40, v115
	s_and_saveexec_b64 s[26:27], vcc
	s_cbranch_execz .LBB0_668
	v_mul_f32_e32 v104, 0xbfb8aa3b, v100
	v_mul_f32_e32 v105, 0xbfb8aa3b, v101
	v_mul_f32_e32 v106, 0xbfb8aa3b, v102
	v_mul_f32_e32 v107, 0xbfb8aa3b, v103
	v_mul_f32_e32 v108, 0xbfb8aa3b, v96
	v_mul_f32_e32 v109, 0xbfb8aa3b, v97
	v_exp_f32_e32 v104, v104
	v_exp_f32_e32 v105, v105
	v_exp_f32_e32 v106, v106
	v_exp_f32_e32 v107, v107
	v_exp_f32_e32 v108, v108
	v_exp_f32_e32 v109, v109
	v_add_f32_e32 v104, 1.0, v104
	v_add_f32_e32 v105, 1.0, v105
	v_add_f32_e32 v106, 1.0, v106
	v_add_f32_e32 v107, 1.0, v107
	v_add_f32_e32 v108, 1.0, v108
	v_add_f32_e32 v109, 1.0, v109
	v_mul_f32_e32 v110, 0xbfb8aa3b, v98
	v_mul_f32_e32 v111, 0xbfb8aa3b, v99
	v_rcp_f32_e32 v104, v104
	v_rcp_f32_e32 v105, v105
	v_rcp_f32_e32 v106, v106
	v_rcp_f32_e32 v107, v107
	v_rcp_f32_e32 v108, v108
	v_exp_f32_e32 v110, v110
	v_exp_f32_e32 v111, v111
	v_rcp_f32_e32 v109, v109
	v_cvt_pk_bf16_f32 v104, v104, v105
	v_add_f32_e32 v110, 1.0, v110
	v_add_f32_e32 v111, 1.0, v111
	v_cvt_pk_bf16_f32 v105, v106, v107
	v_cvt_pk_bf16_f32 v106, v108, v109
	v_lshl_add_u32 v108, v114, 13, v115
	v_rcp_f32_e32 v110, v110
	v_rcp_f32_e32 v111, v111
	v_ashrrev_i32_e32 v109, 31, v108
	v_lshlrev_b64 v[108:109], 12, v[108:109]
	v_lshl_add_u64 v[108:109], v[148:149], 0, v[108:109]
	v_add_co_u32_e32 v108, vcc, 0xfffff000, v108
	v_cvt_pk_bf16_f32 v107, v110, v111
	s_nop 0
	v_addc_co_u32_e32 v109, vcc, -1, v109, vcc
	global_store_dwordx4 v[108:109], v[104:107], off offset:-2304 nt

; __device__ __forceinline__ unsigned pk_bf16(float lo, float hi) { const f32x2 v = {lo, hi}; return __builtin_bit_cast(unsigned, __builtin_convertvector(v, b16x2)); }
; __device__ __forceinline__ float sigmoidf_(float x) { return __builtin_amdgcn_rcpf(1.0f + __expf(-x)); }
;     __device__ __forceinline__ void row(int r, int col32, int fq, const f32x4& a00, const f32x4& a01, const f32x4& a10, const f32x4& a11) const { half(r, col32, fq, a00, a01); half(r, col32 + HALF, fq, a10, a11); }
;     __device__ __forceinline__ void row(int r, int col32, int fq, const f32x4& a00, const f32x4& a01, const f32x4& a10, const f32x4& a11) const { half(r, col32, fq, a00, a01); half(r, col32 + HALF, fq, a10, a11); }
;     __device__ __forceinline__ void row(int r, int col32, int fq, const f32x4& a00, const f32x4& a01, const f32x4& a10, const f32x4& a11) const { half(r, col32, fq, a00, a01); half(r, col32 + HALF, fq, a10, a11); }
;     __device__ __forceinline__ void half(int row, int col32, int fq, const f32x4& v0, const f32x4& v1) const {
;     ...
;             const int col = col32 + 8 * fq, b = row / TP, t = row - b * TP;
;             if (col < 1536) {
;                 const int which = col >> 9, hc = col & 511, h = hc >> 6, d = hc & 63;
;                 const float s = which == 0 ? 0.125f : 1.0f;
;                 u32x4 w; w.x = pk_bf16(v0[0] * s, v0[1] * s); w.y = pk_bf16(v0[2] * s, v0[3] * s); w.z = pk_bf16(v1[0] * s, v1[1] * s); w.w = pk_bf16(v1[2] * s, v1[3] * s);
;                 *(u32x4*)(qkv + (size_t)which * (QKV_ONE / 2) + ((size_t)(b * NH + h) * TP + t) * 64 + d) = w;
;             } else if (t >= NMETA && t < T) {
;                 u32x4 w; w.x = pk_bf16(sigmoidf_(v0[0]), sigmoidf_(v0[1])); w.y = pk_bf16(sigmoidf_(v0[2]), sigmoidf_(v0[3]));
;                 w.z = pk_bf16(sigmoidf_(v1[0]), sigmoidf_(v1[1])); w.w = pk_bf16(sigmoidf_(v1[2]), sigmoidf_(v1[3]));
;                 *(u32x4*)(gates + (size_t)(b * SEQ + t - NMETA) * 2048 + (col - 3328)) = w;
.LBB0_673:
	s_or_b64 exec, exec, s[0:1]
	v_or_b32_e32 v96, 32, v184
	v_mul_hi_i32 v97, v96, s60
	v_lshrrev_b32_e32 v98, 31, v97
	v_ashrrev_i32_e32 v97, 12, v97
	v_add_u32_e32 v98, v97, v98
	v_mad_i32_i24 v96, v98, s61, v96
	v_add_u32_e32 v99, -16, v96
	s_and_saveexec_b64 s[0:1], s[4:5]
	s_xor_b64 s[0:1], exec, s[0:1]
	s_cbranch_execz .LBB0_681
	v_cmp_gt_u32_e32 vcc, s40, v99
	s_and_saveexec_b64 s[26:27], vcc
	s_cbranch_execz .LBB0_676
	v_mul_f32_e32 v101, 0xbfb8aa3b, v94
	v_mul_f32_e32 v102, 0xbfb8aa3b, v95
	v_mul_f32_e32 v103, 0xbfb8aa3b, v88
	v_mul_f32_e32 v104, 0xbfb8aa3b, v89
	v_exp_f32_e32 v101, v101
	v_exp_f32_e32 v102, v102
	v_exp_f32_e32 v103, v103
	v_exp_f32_e32 v104, v104
	v_mul_f32_e32 v105, 0xbfb8aa3b, v90
	v_mul_f32_e32 v106, 0xbfb8aa3b, v91
	v_exp_f32_e32 v105, v105
	v_exp_f32_e32 v106, v106
	v_mul_f32_e32 v97, 0xbfb8aa3b, v92
	v_mul_f32_e32 v100, 0xbfb8aa3b, v93
	v_add_f32_e32 v101, 1.0, v101
	v_add_f32_e32 v102, 1.0, v102
	v_add_f32_e32 v103, 1.0, v103
	v_add_f32_e32 v104, 1.0, v104
	v_exp_f32_e32 v97, v97
	v_exp_f32_e32 v100, v100
	v_rcp_f32_e32 v101, v101
	v_rcp_f32_e32 v102, v102
	v_rcp_f32_e32 v103, v103
	v_rcp_f32_e32 v104, v104
	v_add_f32_e32 v105, 1.0, v105
	v_add_f32_e32 v106, 1.0, v106
	v_rcp_f32_e32 v105, v105
	v_rcp_f32_e32 v106, v106
	v_add_f32_e32 v97, 1.0, v97
	v_add_f32_e32 v100, 1.0, v100
	v_cvt_pk_bf16_f32 v101, v101, v102
	v_cvt_pk_bf16_f32 v102, v103, v104
	v_lshl_add_u32 v104, v98, 13, v99
	v_rcp_f32_e32 v97, v97
	v_rcp_f32_e32 v100, v100
	v_cvt_pk_bf16_f32 v103, v105, v106
	v_ashrrev_i32_e32 v105, 31, v104
	v_lshlrev_b64 v[104:105], 12, v[104:105]
	v_lshl_add_u64 v[104:105], v[148:149], 0, v[104:105]
	v_add_co_u32_e32 v104, vcc, 0xfffff000, v104
	v_cvt_pk_bf16_f32 v100, v97, v100
	s_nop 0
	v_addc_co_u32_e32 v105, vcc, -1, v105, vcc
	global_store_dwordx4 v[104:105], v[100:103], off offset:-2560 nt

; __device__ __forceinline__ unsigned pk_bf16(float lo, float hi) { const f32x2 v = {lo, hi}; return __builtin_bit_cast(unsigned, __builtin_convertvector(v, b16x2)); }
; __device__ __forceinline__ float sigmoidf_(float x) { return __builtin_amdgcn_rcpf(1.0f + __expf(-x)); }
;     __device__ __forceinline__ void half(int row, int col32, int fq, const f32x4& v0, const f32x4& v1) const {
;     ...
;                 u32x4 w; w.x = pk_bf16(v0[0] * s, v0[1] * s); w.y = pk_bf16(v0[2] * s, v0[3] * s); w.z = pk_bf16(v1[0] * s, v1[1] * s); w.w = pk_bf16(v1[2] * s, v1[3] * s);
;                 *(u32x4*)(qkv + (size_t)which * (QKV_ONE / 2) + ((size_t)(b * NH + h) * TP + t) * 64 + d) = w;
;             } else if (t >= NMETA && t < T) {
;                 u32x4 w; w.x = pk_bf16(sigmoidf_(v0[0]), sigmoidf_(v0[1])); w.y = pk_bf16(sigmoidf_(v0[2]), sigmoidf_(v0[3]));
;                 w.z = pk_bf16(sigmoidf_(v1[0]), sigmoidf_(v1[1])); w.w = pk_bf16(sigmoidf_(v1[2]), sigmoidf_(v1[3]));
;                 *(u32x4*)(gates + (size_t)(b * SEQ + t - NMETA) * 2048 + (col - 3328)) = w;
.LBB0_678:
	v_cmp_gt_u32_e32 vcc, s40, v99
	s_and_saveexec_b64 s[26:27], vcc
	s_cbranch_execz .LBB0_680
	v_mul_f32_e32 v88, 0xbfb8aa3b, v84
	v_mul_f32_e32 v89, 0xbfb8aa3b, v85
	v_mul_f32_e32 v90, 0xbfb8aa3b, v86
	v_mul_f32_e32 v91, 0xbfb8aa3b, v87
	v_mul_f32_e32 v92, 0xbfb8aa3b, v80
	v_mul_f32_e32 v93, 0xbfb8aa3b, v81
	v_exp_f32_e32 v88, v88
	v_exp_f32_e32 v89, v89
	v_exp_f32_e32 v90, v90
	v_exp_f32_e32 v91, v91
	v_exp_f32_e32 v92, v92
	v_exp_f32_e32 v93, v93
	v_add_f32_e32 v88, 1.0, v88
	v_add_f32_e32 v89, 1.0, v89
	v_add_f32_e32 v90, 1.0, v90
	v_add_f32_e32 v91, 1.0, v91
	v_add_f32_e32 v92, 1.0, v92
	v_add_f32_e32 v93, 1.0, v93
	v_mul_f32_e32 v94, 0xbfb8aa3b, v82
	v_mul_f32_e32 v95, 0xbfb8aa3b, v83
	v_rcp_f32_e32 v88, v88
	v_rcp_f32_e32 v89, v89
	v_rcp_f32_e32 v90, v90
	v_rcp_f32_e32 v91, v91
	v_rcp_f32_e32 v92, v92
	v_exp_f32_e32 v94, v94
	v_exp_f32_e32 v95, v95
	v_rcp_f32_e32 v93, v93
	v_cvt_pk_bf16_f32 v88, v88, v89
	v_add_f32_e32 v94, 1.0, v94
	v_add_f32_e32 v95, 1.0, v95
	v_cvt_pk_bf16_f32 v89, v90, v91
	v_cvt_pk_bf16_f32 v90, v92, v93
	v_lshl_add_u32 v92, v98, 13, v99
	v_rcp_f32_e32 v94, v94
	v_rcp_f32_e32 v95, v95
	v_ashrrev_i32_e32 v93, 31, v92
	v_lshlrev_b64 v[92:93], 12, v[92:93]
	v_lshl_add_u64 v[92:93], v[148:149], 0, v[92:93]
	v_add_co_u32_e32 v92, vcc, 0xfffff000, v92
	v_cvt_pk_bf16_f32 v91, v94, v95
	s_nop 0
	v_addc_co_u32_e32 v93, vcc, -1, v93, vcc
	global_store_dwordx4 v[92:93], v[88:91], off offset:-2304 nt

; __device__ __forceinline__ unsigned pk_bf16(float lo, float hi) { const f32x2 v = {lo, hi}; return __builtin_bit_cast(unsigned, __builtin_convertvector(v, b16x2)); }
; __device__ __forceinline__ float sigmoidf_(float x) { return __builtin_amdgcn_rcpf(1.0f + __expf(-x)); }
;     __device__ __forceinline__ void row(int r, int col32, int fq, const f32x4& a00, const f32x4& a01, const f32x4& a10, const f32x4& a11) const { half(r, col32, fq, a00, a01); half(r, col32 + HALF, fq, a10, a11); }
;     __device__ __forceinline__ void row(int r, int col32, int fq, const f32x4& a00, const f32x4& a01, const f32x4& a10, const f32x4& a11) const { half(r, col32, fq, a00, a01); half(r, col32 + HALF, fq, a10, a11); }
;     __device__ __forceinline__ void row(int r, int col32, int fq, const f32x4& a00, const f32x4& a01, const f32x4& a10, const f32x4& a11) const { half(r, col32, fq, a00, a01); half(r, col32 + HALF, fq, a10, a11); }
;     __device__ __forceinline__ void half(int row, int col32, int fq, const f32x4& v0, const f32x4& v1) const {
;     ...
;             const int col = col32 + 8 * fq, b = row / TP, t = row - b * TP;
;             if (col < 1536) {
;                 const int which = col >> 9, hc = col & 511, h = hc >> 6, d = hc & 63;
;                 const float s = which == 0 ? 0.125f : 1.0f;
;                 u32x4 w; w.x = pk_bf16(v0[0] * s, v0[1] * s); w.y = pk_bf16(v0[2] * s, v0[3] * s); w.z = pk_bf16(v1[0] * s, v1[1] * s); w.w = pk_bf16(v1[2] * s, v1[3] * s);
;                 *(u32x4*)(qkv + (size_t)which * (QKV_ONE / 2) + ((size_t)(b * NH + h) * TP + t) * 64 + d) = w;
;             } else if (t >= NMETA && t < T) {
;                 u32x4 w; w.x = pk_bf16(sigmoidf_(v0[0]), sigmoidf_(v0[1])); w.y = pk_bf16(sigmoidf_(v0[2]), sigmoidf_(v0[3]));
;                 w.z = pk_bf16(sigmoidf_(v1[0]), sigmoidf_(v1[1])); w.w = pk_bf16(sigmoidf_(v1[2]), sigmoidf_(v1[3]));
;                 *(u32x4*)(gates + (size_t)(b * SEQ + t - NMETA) * 2048 + (col - 3328)) = w;
.LBB0_685:
	s_or_b64 exec, exec, s[0:1]
	v_or_b32_e32 v80, 48, v184
	v_mul_hi_i32 v81, v80, s60
	v_lshrrev_b32_e32 v82, 31, v81
	v_ashrrev_i32_e32 v81, 12, v81
	v_add_u32_e32 v82, v81, v82
	v_mad_i32_i24 v80, v82, s61, v80
	v_add_u32_e32 v83, -16, v80
	s_and_saveexec_b64 s[0:1], s[4:5]
	s_xor_b64 s[0:1], exec, s[0:1]
	s_cbranch_execz .LBB0_693
	v_cmp_gt_u32_e32 vcc, s40, v83
	s_and_saveexec_b64 s[26:27], vcc
	s_cbranch_execz .LBB0_688
	v_mul_f32_e32 v85, 0xbfb8aa3b, v78
	v_mul_f32_e32 v86, 0xbfb8aa3b, v79
	v_mul_f32_e32 v87, 0xbfb8aa3b, v72
	v_mul_f32_e32 v88, 0xbfb8aa3b, v73
	v_exp_f32_e32 v85, v85
	v_exp_f32_e32 v86, v86
	v_exp_f32_e32 v87, v87
	v_exp_f32_e32 v88, v88
	v_mul_f32_e32 v89, 0xbfb8aa3b, v74
	v_mul_f32_e32 v90, 0xbfb8aa3b, v75
	v_exp_f32_e32 v89, v89
	v_exp_f32_e32 v90, v90
	v_mul_f32_e32 v81, 0xbfb8aa3b, v76
	v_mul_f32_e32 v84, 0xbfb8aa3b, v77
	v_add_f32_e32 v85, 1.0, v85
	v_add_f32_e32 v86, 1.0, v86
	v_add_f32_e32 v87, 1.0, v87
	v_add_f32_e32 v88, 1.0, v88
	v_exp_f32_e32 v81, v81
	v_exp_f32_e32 v84, v84
	v_rcp_f32_e32 v85, v85
	v_rcp_f32_e32 v86, v86
	v_rcp_f32_e32 v87, v87
	v_rcp_f32_e32 v88, v88
	v_add_f32_e32 v89, 1.0, v89
	v_add_f32_e32 v90, 1.0, v90
	v_rcp_f32_e32 v89, v89
	v_rcp_f32_e32 v90, v90
	v_add_f32_e32 v81, 1.0, v81
	v_add_f32_e32 v84, 1.0, v84
	v_cvt_pk_bf16_f32 v85, v85, v86
	v_cvt_pk_bf16_f32 v86, v87, v88
	v_lshl_add_u32 v88, v82, 13, v83
	v_rcp_f32_e32 v81, v81
	v_rcp_f32_e32 v84, v84
	v_cvt_pk_bf16_f32 v87, v89, v90
	v_ashrrev_i32_e32 v89, 31, v88
	v_lshlrev_b64 v[88:89], 12, v[88:89]
	v_lshl_add_u64 v[88:89], v[148:149], 0, v[88:89]
	v_add_co_u32_e32 v88, vcc, 0xfffff000, v88
	v_cvt_pk_bf16_f32 v84, v81, v84
	s_nop 0
	v_addc_co_u32_e32 v89, vcc, -1, v89, vcc
	global_store_dwordx4 v[88:89], v[84:87], off offset:-2560 nt

; __device__ __forceinline__ unsigned pk_bf16(float lo, float hi) { const f32x2 v = {lo, hi}; return __builtin_bit_cast(unsigned, __builtin_convertvector(v, b16x2)); }
; __device__ __forceinline__ float sigmoidf_(float x) { return __builtin_amdgcn_rcpf(1.0f + __expf(-x)); }
;     __device__ __forceinline__ void half(int row, int col32, int fq, const f32x4& v0, const f32x4& v1) const {
;     ...
;                 u32x4 w; w.x = pk_bf16(v0[0] * s, v0[1] * s); w.y = pk_bf16(v0[2] * s, v0[3] * s); w.z = pk_bf16(v1[0] * s, v1[1] * s); w.w = pk_bf16(v1[2] * s, v1[3] * s);
;                 *(u32x4*)(qkv + (size_t)which * (QKV_ONE / 2) + ((size_t)(b * NH + h) * TP + t) * 64 + d) = w;
;             } else if (t >= NMETA && t < T) {
;                 u32x4 w; w.x = pk_bf16(sigmoidf_(v0[0]), sigmoidf_(v0[1])); w.y = pk_bf16(sigmoidf_(v0[2]), sigmoidf_(v0[3]));
;                 w.z = pk_bf16(sigmoidf_(v1[0]), sigmoidf_(v1[1])); w.w = pk_bf16(sigmoidf_(v1[2]), sigmoidf_(v1[3]));
;                 *(u32x4*)(gates + (size_t)(b * SEQ + t - NMETA) * 2048 + (col - 3328)) = w;
.LBB0_690:
	v_cmp_gt_u32_e32 vcc, s40, v83
	s_and_saveexec_b64 s[26:27], vcc
	s_cbranch_execz .LBB0_692
	v_mul_f32_e32 v72, 0xbfb8aa3b, v68
	v_mul_f32_e32 v73, 0xbfb8aa3b, v69
	v_mul_f32_e32 v74, 0xbfb8aa3b, v70
	v_mul_f32_e32 v75, 0xbfb8aa3b, v71
	v_mul_f32_e32 v76, 0xbfb8aa3b, v64
	v_mul_f32_e32 v77, 0xbfb8aa3b, v65
	v_exp_f32_e32 v72, v72
	v_exp_f32_e32 v73, v73
	v_exp_f32_e32 v74, v74
	v_exp_f32_e32 v75, v75
	v_exp_f32_e32 v76, v76
	v_exp_f32_e32 v77, v77
	v_add_f32_e32 v72, 1.0, v72
	v_add_f32_e32 v73, 1.0, v73
	v_add_f32_e32 v74, 1.0, v74
	v_add_f32_e32 v75, 1.0, v75
	v_add_f32_e32 v76, 1.0, v76
	v_add_f32_e32 v77, 1.0, v77
	v_mul_f32_e32 v78, 0xbfb8aa3b, v66
	v_mul_f32_e32 v79, 0xbfb8aa3b, v67
	v_rcp_f32_e32 v72, v72
	v_rcp_f32_e32 v73, v73
	v_rcp_f32_e32 v74, v74
	v_rcp_f32_e32 v75, v75
	v_rcp_f32_e32 v76, v76
	v_exp_f32_e32 v78, v78
	v_exp_f32_e32 v79, v79
	v_rcp_f32_e32 v77, v77
	v_cvt_pk_bf16_f32 v72, v72, v73
	v_add_f32_e32 v78, 1.0, v78
	v_add_f32_e32 v79, 1.0, v79
	v_cvt_pk_bf16_f32 v73, v74, v75
	v_cvt_pk_bf16_f32 v74, v76, v77
	v_lshl_add_u32 v76, v82, 13, v83
	v_rcp_f32_e32 v78, v78
	v_rcp_f32_e32 v79, v79
	v_ashrrev_i32_e32 v77, 31, v76
	v_lshlrev_b64 v[76:77], 12, v[76:77]
	v_lshl_add_u64 v[76:77], v[148:149], 0, v[76:77]
	v_add_co_u32_e32 v76, vcc, 0xfffff000, v76
	v_cvt_pk_bf16_f32 v75, v78, v79
	s_nop 0
	v_addc_co_u32_e32 v77, vcc, -1, v77, vcc
	global_store_dwordx4 v[76:77], v[72:75], off offset:-2304 nt

; __device__ __forceinline__ unsigned pk_bf16(float lo, float hi) { const f32x2 v = {lo, hi}; return __builtin_bit_cast(unsigned, __builtin_convertvector(v, b16x2)); }
; __device__ __forceinline__ float sigmoidf_(float x) { return __builtin_amdgcn_rcpf(1.0f + __expf(-x)); }
;     __device__ __forceinline__ void row(int r, int col32, int fq, const f32x4& a00, const f32x4& a01, const f32x4& a10, const f32x4& a11) const { half(r, col32, fq, a00, a01); half(r, col32 + HALF, fq, a10, a11); }
;     __device__ __forceinline__ void row(int r, int col32, int fq, const f32x4& a00, const f32x4& a01, const f32x4& a10, const f32x4& a11) const { half(r, col32, fq, a00, a01); half(r, col32 + HALF, fq, a10, a11); }
;     __device__ __forceinline__ void row(int r, int col32, int fq, const f32x4& a00, const f32x4& a01, const f32x4& a10, const f32x4& a11) const { half(r, col32, fq, a00, a01); half(r, col32 + HALF, fq, a10, a11); }
;     __device__ __forceinline__ void half(int row, int col32, int fq, const f32x4& v0, const f32x4& v1) const {
;     ...
;             const int col = col32 + 8 * fq, b = row / TP, t = row - b * TP;
;             if (col < 1536) {
;                 const int which = col >> 9, hc = col & 511, h = hc >> 6, d = hc & 63;
;                 const float s = which == 0 ? 0.125f : 1.0f;
;                 u32x4 w; w.x = pk_bf16(v0[0] * s, v0[1] * s); w.y = pk_bf16(v0[2] * s, v0[3] * s); w.z = pk_bf16(v1[0] * s, v1[1] * s); w.w = pk_bf16(v1[2] * s, v1[3] * s);
;                 *(u32x4*)(qkv + (size_t)which * (QKV_ONE / 2) + ((size_t)(b * NH + h) * TP + t) * 64 + d) = w;
;             } else if (t >= NMETA && t < T) {
;                 u32x4 w; w.x = pk_bf16(sigmoidf_(v0[0]), sigmoidf_(v0[1])); w.y = pk_bf16(sigmoidf_(v0[2]), sigmoidf_(v0[3]));
;                 w.z = pk_bf16(sigmoidf_(v1[0]), sigmoidf_(v1[1])); w.w = pk_bf16(sigmoidf_(v1[2]), sigmoidf_(v1[3]));
;                 *(u32x4*)(gates + (size_t)(b * SEQ + t - NMETA) * 2048 + (col - 3328)) = w;
.LBB0_697:
	s_or_b64 exec, exec, s[0:1]
	v_add_u32_e32 v64, 0x80, v184
	v_mul_hi_i32 v65, v64, s60
	v_lshrrev_b32_e32 v66, 31, v65
	v_ashrrev_i32_e32 v65, 12, v65
	v_add_u32_e32 v66, v65, v66
	v_mad_i32_i24 v64, v66, s61, v64
	v_add_u32_e32 v67, -16, v64
	s_and_saveexec_b64 s[0:1], s[4:5]
	s_xor_b64 s[0:1], exec, s[0:1]
	s_cbranch_execz .LBB0_705
	v_cmp_gt_u32_e32 vcc, s40, v67
	s_and_saveexec_b64 s[26:27], vcc
	s_cbranch_execz .LBB0_700
	v_mul_f32_e32 v69, 0xbfb8aa3b, v62
	v_mul_f32_e32 v70, 0xbfb8aa3b, v63
	v_mul_f32_e32 v71, 0xbfb8aa3b, v56
	v_mul_f32_e32 v72, 0xbfb8aa3b, v57
	v_exp_f32_e32 v69, v69
	v_exp_f32_e32 v70, v70
	v_exp_f32_e32 v71, v71
	v_exp_f32_e32 v72, v72
	v_mul_f32_e32 v73, 0xbfb8aa3b, v58
	v_mul_f32_e32 v74, 0xbfb8aa3b, v59
	v_exp_f32_e32 v73, v73
	v_exp_f32_e32 v74, v74
	v_mul_f32_e32 v65, 0xbfb8aa3b, v60
	v_mul_f32_e32 v68, 0xbfb8aa3b, v61
	v_add_f32_e32 v69, 1.0, v69
	v_add_f32_e32 v70, 1.0, v70
	v_add_f32_e32 v71, 1.0, v71
	v_add_f32_e32 v72, 1.0, v72
	v_exp_f32_e32 v65, v65
	v_exp_f32_e32 v68, v68
	v_rcp_f32_e32 v69, v69
	v_rcp_f32_e32 v70, v70
	v_rcp_f32_e32 v71, v71
	v_rcp_f32_e32 v72, v72
	v_add_f32_e32 v73, 1.0, v73
	v_add_f32_e32 v74, 1.0, v74
	v_rcp_f32_e32 v73, v73
	v_rcp_f32_e32 v74, v74
	v_add_f32_e32 v65, 1.0, v65
	v_add_f32_e32 v68, 1.0, v68
	v_cvt_pk_bf16_f32 v69, v69, v70
	v_cvt_pk_bf16_f32 v70, v71, v72
	v_lshl_add_u32 v72, v66, 13, v67
	v_rcp_f32_e32 v65, v65
	v_rcp_f32_e32 v68, v68
	v_cvt_pk_bf16_f32 v71, v73, v74
	v_ashrrev_i32_e32 v73, 31, v72
	v_lshlrev_b64 v[72:73], 12, v[72:73]
	v_lshl_add_u64 v[72:73], v[148:149], 0, v[72:73]
	v_add_co_u32_e32 v72, vcc, 0xfffff000, v72
	v_cvt_pk_bf16_f32 v68, v65, v68
	s_nop 0
	v_addc_co_u32_e32 v73, vcc, -1, v73, vcc
	global_store_dwordx4 v[72:73], v[68:71], off offset:-2560 nt

; __device__ __forceinline__ unsigned pk_bf16(float lo, float hi) { const f32x2 v = {lo, hi}; return __builtin_bit_cast(unsigned, __builtin_convertvector(v, b16x2)); }
; __device__ __forceinline__ float sigmoidf_(float x) { return __builtin_amdgcn_rcpf(1.0f + __expf(-x)); }
;     __device__ __forceinline__ void half(int row, int col32, int fq, const f32x4& v0, const f32x4& v1) const {
;     ...
;                 u32x4 w; w.x = pk_bf16(v0[0] * s, v0[1] * s); w.y = pk_bf16(v0[2] * s, v0[3] * s); w.z = pk_bf16(v1[0] * s, v1[1] * s); w.w = pk_bf16(v1[2] * s, v1[3] * s);
;                 *(u32x4*)(qkv + (size_t)which * (QKV_ONE / 2) + ((size_t)(b * NH + h) * TP + t) * 64 + d) = w;
;             } else if (t >= NMETA && t < T) {
;                 u32x4 w; w.x = pk_bf16(sigmoidf_(v0[0]), sigmoidf_(v0[1])); w.y = pk_bf16(sigmoidf_(v0[2]), sigmoidf_(v0[3]));
;                 w.z = pk_bf16(sigmoidf_(v1[0]), sigmoidf_(v1[1])); w.w = pk_bf16(sigmoidf_(v1[2]), sigmoidf_(v1[3]));
;                 *(u32x4*)(gates + (size_t)(b * SEQ + t - NMETA) * 2048 + (col - 3328)) = w;
.LBB0_702:
	v_cmp_gt_u32_e32 vcc, s40, v67
	s_and_saveexec_b64 s[26:27], vcc
	s_cbranch_execz .LBB0_704
	v_mul_f32_e32 v56, 0xbfb8aa3b, v52
	v_mul_f32_e32 v57, 0xbfb8aa3b, v53
	v_mul_f32_e32 v58, 0xbfb8aa3b, v54
	v_mul_f32_e32 v59, 0xbfb8aa3b, v55
	v_mul_f32_e32 v60, 0xbfb8aa3b, v48
	v_mul_f32_e32 v61, 0xbfb8aa3b, v49
	v_exp_f32_e32 v56, v56
	v_exp_f32_e32 v57, v57
	v_exp_f32_e32 v58, v58
	v_exp_f32_e32 v59, v59
	v_exp_f32_e32 v60, v60
	v_exp_f32_e32 v61, v61
	v_add_f32_e32 v56, 1.0, v56
	v_add_f32_e32 v57, 1.0, v57
	v_add_f32_e32 v58, 1.0, v58
	v_add_f32_e32 v59, 1.0, v59
	v_add_f32_e32 v60, 1.0, v60
	v_add_f32_e32 v61, 1.0, v61
	v_mul_f32_e32 v62, 0xbfb8aa3b, v50
	v_mul_f32_e32 v63, 0xbfb8aa3b, v51
	v_rcp_f32_e32 v56, v56
	v_rcp_f32_e32 v57, v57
	v_rcp_f32_e32 v58, v58
	v_rcp_f32_e32 v59, v59
	v_rcp_f32_e32 v60, v60
	v_exp_f32_e32 v62, v62
	v_exp_f32_e32 v63, v63
	v_rcp_f32_e32 v61, v61
	v_cvt_pk_bf16_f32 v56, v56, v57
	v_add_f32_e32 v62, 1.0, v62
	v_add_f32_e32 v63, 1.0, v63
	v_cvt_pk_bf16_f32 v57, v58, v59
	v_cvt_pk_bf16_f32 v58, v60, v61
	v_lshl_add_u32 v60, v66, 13, v67
	v_rcp_f32_e32 v62, v62
	v_rcp_f32_e32 v63, v63
	v_ashrrev_i32_e32 v61, 31, v60
	v_lshlrev_b64 v[60:61], 12, v[60:61]
	v_lshl_add_u64 v[60:61], v[148:149], 0, v[60:61]
	v_add_co_u32_e32 v60, vcc, 0xfffff000, v60
	v_cvt_pk_bf16_f32 v59, v62, v63
	s_nop 0
	v_addc_co_u32_e32 v61, vcc, -1, v61, vcc
	global_store_dwordx4 v[60:61], v[56:59], off offset:-2304 nt

; __device__ __forceinline__ unsigned pk_bf16(float lo, float hi) { const f32x2 v = {lo, hi}; return __builtin_bit_cast(unsigned, __builtin_convertvector(v, b16x2)); }
; __device__ __forceinline__ float sigmoidf_(float x) { return __builtin_amdgcn_rcpf(1.0f + __expf(-x)); }
;     __device__ __forceinline__ void row(int r, int col32, int fq, const f32x4& a00, const f32x4& a01, const f32x4& a10, const f32x4& a11) const { half(r, col32, fq, a00, a01); half(r, col32 + HALF, fq, a10, a11); }
;     __device__ __forceinline__ void row(int r, int col32, int fq, const f32x4& a00, const f32x4& a01, const f32x4& a10, const f32x4& a11) const { half(r, col32, fq, a00, a01); half(r, col32 + HALF, fq, a10, a11); }
;     __device__ __forceinline__ void row(int r, int col32, int fq, const f32x4& a00, const f32x4& a01, const f32x4& a10, const f32x4& a11) const { half(r, col32, fq, a00, a01); half(r, col32 + HALF, fq, a10, a11); }
;     __device__ __forceinline__ void half(int row, int col32, int fq, const f32x4& v0, const f32x4& v1) const {
;     ...
;             const int col = col32 + 8 * fq, b = row / TP, t = row - b * TP;
;             if (col < 1536) {
;                 const int which = col >> 9, hc = col & 511, h = hc >> 6, d = hc & 63;
;                 const float s = which == 0 ? 0.125f : 1.0f;
;                 u32x4 w; w.x = pk_bf16(v0[0] * s, v0[1] * s); w.y = pk_bf16(v0[2] * s, v0[3] * s); w.z = pk_bf16(v1[0] * s, v1[1] * s); w.w = pk_bf16(v1[2] * s, v1[3] * s);
;                 *(u32x4*)(qkv + (size_t)which * (QKV_ONE / 2) + ((size_t)(b * NH + h) * TP + t) * 64 + d) = w;
;             } else if (t >= NMETA && t < T) {
;                 u32x4 w; w.x = pk_bf16(sigmoidf_(v0[0]), sigmoidf_(v0[1])); w.y = pk_bf16(sigmoidf_(v0[2]), sigmoidf_(v0[3]));
;                 w.z = pk_bf16(sigmoidf_(v1[0]), sigmoidf_(v1[1])); w.w = pk_bf16(sigmoidf_(v1[2]), sigmoidf_(v1[3]));
;                 *(u32x4*)(gates + (size_t)(b * SEQ + t - NMETA) * 2048 + (col - 3328)) = w;
.LBB0_709:
	s_or_b64 exec, exec, s[0:1]
	v_add_u32_e32 v48, 0x90, v184
	v_mul_hi_i32 v49, v48, s60
	v_lshrrev_b32_e32 v50, 31, v49
	v_ashrrev_i32_e32 v49, 12, v49
	v_add_u32_e32 v50, v49, v50
	v_mad_i32_i24 v48, v50, s61, v48
	v_add_u32_e32 v51, -16, v48
	s_and_saveexec_b64 s[0:1], s[4:5]
	s_xor_b64 s[0:1], exec, s[0:1]
	s_cbranch_execz .LBB0_717
	v_cmp_gt_u32_e32 vcc, s40, v51
	s_and_saveexec_b64 s[26:27], vcc
	s_cbranch_execz .LBB0_712
	v_mul_f32_e32 v53, 0xbfb8aa3b, v46
	v_mul_f32_e32 v54, 0xbfb8aa3b, v47
	v_mul_f32_e32 v55, 0xbfb8aa3b, v40
	v_mul_f32_e32 v56, 0xbfb8aa3b, v41
	v_exp_f32_e32 v53, v53
	v_exp_f32_e32 v54, v54
	v_exp_f32_e32 v55, v55
	v_exp_f32_e32 v56, v56
	v_mul_f32_e32 v57, 0xbfb8aa3b, v42
	v_mul_f32_e32 v58, 0xbfb8aa3b, v43
	v_exp_f32_e32 v57, v57
	v_exp_f32_e32 v58, v58
	v_mul_f32_e32 v49, 0xbfb8aa3b, v44
	v_mul_f32_e32 v52, 0xbfb8aa3b, v45
	v_add_f32_e32 v53, 1.0, v53
	v_add_f32_e32 v54, 1.0, v54
	v_add_f32_e32 v55, 1.0, v55
	v_add_f32_e32 v56, 1.0, v56
	v_exp_f32_e32 v49, v49
	v_exp_f32_e32 v52, v52
	v_rcp_f32_e32 v53, v53
	v_rcp_f32_e32 v54, v54
	v_rcp_f32_e32 v55, v55
	v_rcp_f32_e32 v56, v56
	v_add_f32_e32 v57, 1.0, v57
	v_add_f32_e32 v58, 1.0, v58
	v_rcp_f32_e32 v57, v57
	v_rcp_f32_e32 v58, v58
	v_add_f32_e32 v49, 1.0, v49
	v_add_f32_e32 v52, 1.0, v52
	v_cvt_pk_bf16_f32 v53, v53, v54
	v_cvt_pk_bf16_f32 v54, v55, v56
	v_lshl_add_u32 v56, v50, 13, v51
	v_rcp_f32_e32 v49, v49
	v_rcp_f32_e32 v52, v52
	v_cvt_pk_bf16_f32 v55, v57, v58
	v_ashrrev_i32_e32 v57, 31, v56
	v_lshlrev_b64 v[56:57], 12, v[56:57]
	v_lshl_add_u64 v[56:57], v[148:149], 0, v[56:57]
	v_add_co_u32_e32 v56, vcc, 0xfffff000, v56
	v_cvt_pk_bf16_f32 v52, v49, v52
	s_nop 0
	v_addc_co_u32_e32 v57, vcc, -1, v57, vcc
	global_store_dwordx4 v[56:57], v[52:55], off offset:-2560 nt

; __device__ __forceinline__ unsigned pk_bf16(float lo, float hi) { const f32x2 v = {lo, hi}; return __builtin_bit_cast(unsigned, __builtin_convertvector(v, b16x2)); }
; __device__ __forceinline__ float sigmoidf_(float x) { return __builtin_amdgcn_rcpf(1.0f + __expf(-x)); }
;     __device__ __forceinline__ void half(int row, int col32, int fq, const f32x4& v0, const f32x4& v1) const {
;     ...
;                 u32x4 w; w.x = pk_bf16(v0[0] * s, v0[1] * s); w.y = pk_bf16(v0[2] * s, v0[3] * s); w.z = pk_bf16(v1[0] * s, v1[1] * s); w.w = pk_bf16(v1[2] * s, v1[3] * s);
;                 *(u32x4*)(qkv + (size_t)which * (QKV_ONE / 2) + ((size_t)(b * NH + h) * TP + t) * 64 + d) = w;
;             } else if (t >= NMETA && t < T) {
;                 u32x4 w; w.x = pk_bf16(sigmoidf_(v0[0]), sigmoidf_(v0[1])); w.y = pk_bf16(sigmoidf_(v0[2]), sigmoidf_(v0[3]));
;                 w.z = pk_bf16(sigmoidf_(v1[0]), sigmoidf_(v1[1])); w.w = pk_bf16(sigmoidf_(v1[2]), sigmoidf_(v1[3]));
;                 *(u32x4*)(gates + (size_t)(b * SEQ + t - NMETA) * 2048 + (col - 3328)) = w;
.LBB0_714:
	v_cmp_gt_u32_e32 vcc, s40, v51
	s_and_saveexec_b64 s[26:27], vcc
	s_cbranch_execz .LBB0_716
	v_mul_f32_e32 v40, 0xbfb8aa3b, v36
	v_mul_f32_e32 v41, 0xbfb8aa3b, v37
	v_mul_f32_e32 v42, 0xbfb8aa3b, v38
	v_mul_f32_e32 v43, 0xbfb8aa3b, v39
	v_mul_f32_e32 v44, 0xbfb8aa3b, v32
	v_mul_f32_e32 v45, 0xbfb8aa3b, v33
	v_exp_f32_e32 v40, v40
	v_exp_f32_e32 v41, v41
	v_exp_f32_e32 v42, v42
	v_exp_f32_e32 v43, v43
	v_exp_f32_e32 v44, v44
	v_exp_f32_e32 v45, v45
	v_add_f32_e32 v40, 1.0, v40
	v_add_f32_e32 v41, 1.0, v41
	v_add_f32_e32 v42, 1.0, v42
	v_add_f32_e32 v43, 1.0, v43
	v_add_f32_e32 v44, 1.0, v44
	v_add_f32_e32 v45, 1.0, v45
	v_mul_f32_e32 v46, 0xbfb8aa3b, v34
	v_mul_f32_e32 v47, 0xbfb8aa3b, v35
	v_rcp_f32_e32 v40, v40
	v_rcp_f32_e32 v41, v41
	v_rcp_f32_e32 v42, v42
	v_rcp_f32_e32 v43, v43
	v_rcp_f32_e32 v44, v44
	v_exp_f32_e32 v46, v46
	v_exp_f32_e32 v47, v47
	v_rcp_f32_e32 v45, v45
	v_cvt_pk_bf16_f32 v40, v40, v41
	v_add_f32_e32 v46, 1.0, v46
	v_add_f32_e32 v47, 1.0, v47
	v_cvt_pk_bf16_f32 v41, v42, v43
	v_cvt_pk_bf16_f32 v42, v44, v45
	v_lshl_add_u32 v44, v50, 13, v51
	v_rcp_f32_e32 v46, v46
	v_rcp_f32_e32 v47, v47
	v_ashrrev_i32_e32 v45, 31, v44
	v_lshlrev_b64 v[44:45], 12, v[44:45]
	v_lshl_add_u64 v[44:45], v[148:149], 0, v[44:45]
	v_add_co_u32_e32 v44, vcc, 0xfffff000, v44
	v_cvt_pk_bf16_f32 v43, v46, v47
	s_nop 0
	v_addc_co_u32_e32 v45, vcc, -1, v45, vcc
	global_store_dwordx4 v[44:45], v[40:43], off offset:-2304 nt

; __device__ __forceinline__ unsigned pk_bf16(float lo, float hi) { const f32x2 v = {lo, hi}; return __builtin_bit_cast(unsigned, __builtin_convertvector(v, b16x2)); }
; __device__ __forceinline__ float sigmoidf_(float x) { return __builtin_amdgcn_rcpf(1.0f + __expf(-x)); }
;     __device__ __forceinline__ void row(int r, int col32, int fq, const f32x4& a00, const f32x4& a01, const f32x4& a10, const f32x4& a11) const { half(r, col32, fq, a00, a01); half(r, col32 + HALF, fq, a10, a11); }
;     __device__ __forceinline__ void row(int r, int col32, int fq, const f32x4& a00, const f32x4& a01, const f32x4& a10, const f32x4& a11) const { half(r, col32, fq, a00, a01); half(r, col32 + HALF, fq, a10, a11); }
;     __device__ __forceinline__ void row(int r, int col32, int fq, const f32x4& a00, const f32x4& a01, const f32x4& a10, const f32x4& a11) const { half(r, col32, fq, a00, a01); half(r, col32 + HALF, fq, a10, a11); }
;     __device__ __forceinline__ void half(int row, int col32, int fq, const f32x4& v0, const f32x4& v1) const {
;     ...
;             const int col = col32 + 8 * fq, b = row / TP, t = row - b * TP;
;             if (col < 1536) {
;                 const int which = col >> 9, hc = col & 511, h = hc >> 6, d = hc & 63;
;                 const float s = which == 0 ? 0.125f : 1.0f;
;                 u32x4 w; w.x = pk_bf16(v0[0] * s, v0[1] * s); w.y = pk_bf16(v0[2] * s, v0[3] * s); w.z = pk_bf16(v1[0] * s, v1[1] * s); w.w = pk_bf16(v1[2] * s, v1[3] * s);
;                 *(u32x4*)(qkv + (size_t)which * (QKV_ONE / 2) + ((size_t)(b * NH + h) * TP + t) * 64 + d) = w;
;             } else if (t >= NMETA && t < T) {
;                 u32x4 w; w.x = pk_bf16(sigmoidf_(v0[0]), sigmoidf_(v0[1])); w.y = pk_bf16(sigmoidf_(v0[2]), sigmoidf_(v0[3]));
;                 w.z = pk_bf16(sigmoidf_(v1[0]), sigmoidf_(v1[1])); w.w = pk_bf16(sigmoidf_(v1[2]), sigmoidf_(v1[3]));
;                 *(u32x4*)(gates + (size_t)(b * SEQ + t - NMETA) * 2048 + (col - 3328)) = w;
;             }
.LBB0_721:
	s_or_b64 exec, exec, s[0:1]
	v_add_u32_e32 v32, 0xa0, v184
	v_mul_hi_i32 v33, v32, s60
	v_lshrrev_b32_e32 v34, 31, v33
	v_ashrrev_i32_e32 v33, 12, v33
	v_add_u32_e32 v34, v33, v34
	v_mad_i32_i24 v32, v34, s61, v32
	v_add_u32_e32 v35, -16, v32
	s_and_saveexec_b64 s[0:1], s[4:5]
	s_xor_b64 s[0:1], exec, s[0:1]
	s_cbranch_execz .LBB0_729
	v_cmp_gt_u32_e32 vcc, s40, v35
	s_and_saveexec_b64 s[26:27], vcc
	s_cbranch_execz .LBB0_724
	v_mul_f32_e32 v37, 0xbfb8aa3b, v30
	v_mul_f32_e32 v38, 0xbfb8aa3b, v31
	v_mul_f32_e32 v39, 0xbfb8aa3b, v24
	v_mul_f32_e32 v40, 0xbfb8aa3b, v25
	v_exp_f32_e32 v37, v37
	v_exp_f32_e32 v38, v38
	v_exp_f32_e32 v39, v39
	v_exp_f32_e32 v40, v40
	v_mul_f32_e32 v41, 0xbfb8aa3b, v26
	v_mul_f32_e32 v42, 0xbfb8aa3b, v27
	v_exp_f32_e32 v41, v41
	v_exp_f32_e32 v42, v42
	v_mul_f32_e32 v33, 0xbfb8aa3b, v28
	v_mul_f32_e32 v36, 0xbfb8aa3b, v29
	v_add_f32_e32 v37, 1.0, v37
	v_add_f32_e32 v38, 1.0, v38
	v_add_f32_e32 v39, 1.0, v39
	v_add_f32_e32 v40, 1.0, v40
	v_exp_f32_e32 v33, v33
	v_exp_f32_e32 v36, v36
	v_rcp_f32_e32 v37, v37
	v_rcp_f32_e32 v38, v38
	v_rcp_f32_e32 v39, v39
	v_rcp_f32_e32 v40, v40
	v_add_f32_e32 v41, 1.0, v41
	v_add_f32_e32 v42, 1.0, v42
	v_rcp_f32_e32 v41, v41
	v_rcp_f32_e32 v42, v42
	v_add_f32_e32 v33, 1.0, v33
	v_add_f32_e32 v36, 1.0, v36
	v_cvt_pk_bf16_f32 v37, v37, v38
	v_cvt_pk_bf16_f32 v38, v39, v40
	v_lshl_add_u32 v40, v34, 13, v35
	v_rcp_f32_e32 v33, v33
	v_rcp_f32_e32 v36, v36
	v_cvt_pk_bf16_f32 v39, v41, v42
	v_ashrrev_i32_e32 v41, 31, v40
	v_lshlrev_b64 v[40:41], 12, v[40:41]
	v_lshl_add_u64 v[40:41], v[148:149], 0, v[40:41]
	v_add_co_u32_e32 v40, vcc, 0xfffff000, v40
	v_cvt_pk_bf16_f32 v36, v33, v36
	s_nop 0
	v_addc_co_u32_e32 v41, vcc, -1, v41, vcc
	global_store_dwordx4 v[40:41], v[36:39], off offset:-2560 nt

; __device__ __forceinline__ unsigned pk_bf16(float lo, float hi) { const f32x2 v = {lo, hi}; return __builtin_bit_cast(unsigned, __builtin_convertvector(v, b16x2)); }
; __device__ __forceinline__ float sigmoidf_(float x) { return __builtin_amdgcn_rcpf(1.0f + __expf(-x)); }
;     __device__ __forceinline__ void half(int row, int col32, int fq, const f32x4& v0, const f32x4& v1) const {
;     ...
;             } else if (t >= NMETA && t < T) {
;                 u32x4 w; w.x = pk_bf16(sigmoidf_(v0[0]), sigmoidf_(v0[1])); w.y = pk_bf16(sigmoidf_(v0[2]), sigmoidf_(v0[3]));
;                 w.z = pk_bf16(sigmoidf_(v1[0]), sigmoidf_(v1[1])); w.w = pk_bf16(sigmoidf_(v1[2]), sigmoidf_(v1[3]));
;                 *(u32x4*)(gates + (size_t)(b * SEQ + t - NMETA) * 2048 + (col - 3328)) = w;
;             }
.LBB0_726:
	v_cmp_gt_u32_e32 vcc, s40, v35
	s_and_saveexec_b64 s[26:27], vcc
	s_cbranch_execz .LBB0_728
	v_mul_f32_e32 v24, 0xbfb8aa3b, v20
	v_mul_f32_e32 v25, 0xbfb8aa3b, v21
	v_mul_f32_e32 v26, 0xbfb8aa3b, v22
	v_mul_f32_e32 v27, 0xbfb8aa3b, v23
	v_mul_f32_e32 v28, 0xbfb8aa3b, v16
	v_mul_f32_e32 v29, 0xbfb8aa3b, v17
	v_exp_f32_e32 v24, v24
	v_exp_f32_e32 v25, v25
	v_exp_f32_e32 v26, v26
	v_exp_f32_e32 v27, v27
	v_exp_f32_e32 v28, v28
	v_exp_f32_e32 v29, v29
	v_add_f32_e32 v24, 1.0, v24
	v_add_f32_e32 v25, 1.0, v25
	v_add_f32_e32 v26, 1.0, v26
	v_add_f32_e32 v27, 1.0, v27
	v_add_f32_e32 v28, 1.0, v28
	v_add_f32_e32 v29, 1.0, v29
	v_mul_f32_e32 v30, 0xbfb8aa3b, v18
	v_mul_f32_e32 v31, 0xbfb8aa3b, v19
	v_rcp_f32_e32 v24, v24
	v_rcp_f32_e32 v25, v25
	v_rcp_f32_e32 v26, v26
	v_rcp_f32_e32 v27, v27
	v_rcp_f32_e32 v28, v28
	v_exp_f32_e32 v30, v30
	v_exp_f32_e32 v31, v31
	v_rcp_f32_e32 v29, v29
	v_cvt_pk_bf16_f32 v24, v24, v25
	v_add_f32_e32 v30, 1.0, v30
	v_add_f32_e32 v31, 1.0, v31
	v_cvt_pk_bf16_f32 v25, v26, v27
	v_cvt_pk_bf16_f32 v26, v28, v29
	v_lshl_add_u32 v28, v34, 13, v35
	v_rcp_f32_e32 v30, v30
	v_rcp_f32_e32 v31, v31
	v_ashrrev_i32_e32 v29, 31, v28
	v_lshlrev_b64 v[28:29], 12, v[28:29]
	v_lshl_add_u64 v[28:29], v[148:149], 0, v[28:29]
	v_add_co_u32_e32 v28, vcc, 0xfffff000, v28
	v_cvt_pk_bf16_f32 v27, v30, v31
	s_nop 0
	v_addc_co_u32_e32 v29, vcc, -1, v29, vcc
	global_store_dwordx4 v[28:29], v[24:27], off offset:-2304 nt

; __device__ __forceinline__ unsigned pk_bf16(float lo, float hi) { const f32x2 v = {lo, hi}; return __builtin_bit_cast(unsigned, __builtin_convertvector(v, b16x2)); }
; __device__ __forceinline__ float sigmoidf_(float x) { return __builtin_amdgcn_rcpf(1.0f + __expf(-x)); }
;     __device__ __forceinline__ void row(int r, int col32, int fq, const f32x4& a00, const f32x4& a01, const f32x4& a10, const f32x4& a11) const { half(r, col32, fq, a00, a01); half(r, col32 + HALF, fq, a10, a11); }
;     __device__ __forceinline__ void row(int r, int col32, int fq, const f32x4& a00, const f32x4& a01, const f32x4& a10, const f32x4& a11) const { half(r, col32, fq, a00, a01); half(r, col32 + HALF, fq, a10, a11); }
;     __device__ __forceinline__ void row(int r, int col32, int fq, const f32x4& a00, const f32x4& a01, const f32x4& a10, const f32x4& a11) const { half(r, col32, fq, a00, a01); half(r, col32 + HALF, fq, a10, a11); }
;     __device__ __forceinline__ void half(int row, int col32, int fq, const f32x4& v0, const f32x4& v1) const {
;     ...
;             const int col = col32 + 8 * fq, b = row / TP, t = row - b * TP;
;             if (col < 1536) {
;                 const int which = col >> 9, hc = col & 511, h = hc >> 6, d = hc & 63;
;                 const float s = which == 0 ? 0.125f : 1.0f;
;                 u32x4 w; w.x = pk_bf16(v0[0] * s, v0[1] * s); w.y = pk_bf16(v0[2] * s, v0[3] * s); w.z = pk_bf16(v1[0] * s, v1[1] * s); w.w = pk_bf16(v1[2] * s, v1[3] * s);
;                 *(u32x4*)(qkv + (size_t)which * (QKV_ONE / 2) + ((size_t)(b * NH + h) * TP + t) * 64 + d) = w;
;             } else if (t >= NMETA && t < T) {
;                 u32x4 w; w.x = pk_bf16(sigmoidf_(v0[0]), sigmoidf_(v0[1])); w.y = pk_bf16(sigmoidf_(v0[2]), sigmoidf_(v0[3]));
;                 w.z = pk_bf16(sigmoidf_(v1[0]), sigmoidf_(v1[1])); w.w = pk_bf16(sigmoidf_(v1[2]), sigmoidf_(v1[3]));
;                 *(u32x4*)(gates + (size_t)(b * SEQ + t - NMETA) * 2048 + (col - 3328)) = w;
;             }
.LBB0_733:
	s_or_b64 exec, exec, s[0:1]
	v_add_u32_e32 v16, 0xb0, v184
	v_mul_hi_i32 v17, v16, s60
	v_lshrrev_b32_e32 v18, 31, v17
	v_ashrrev_i32_e32 v17, 12, v17
	v_add_u32_e32 v18, v17, v18
	v_mad_i32_i24 v16, v18, s61, v16
	v_add_u32_e32 v19, -16, v16
	s_and_saveexec_b64 s[0:1], s[4:5]
	s_xor_b64 s[0:1], exec, s[0:1]
	s_cbranch_execz .LBB0_741
	v_cmp_gt_u32_e32 vcc, s40, v19
	s_and_saveexec_b64 s[4:5], vcc
	s_cbranch_execz .LBB0_736
	v_mul_f32_e32 v21, 0xbfb8aa3b, v14
	v_mul_f32_e32 v22, 0xbfb8aa3b, v15
	v_mul_f32_e32 v23, 0xbfb8aa3b, v8
	v_mul_f32_e32 v24, 0xbfb8aa3b, v9
	v_exp_f32_e32 v21, v21
	v_exp_f32_e32 v22, v22
	v_exp_f32_e32 v23, v23
	v_exp_f32_e32 v24, v24
	v_mul_f32_e32 v25, 0xbfb8aa3b, v10
	v_mul_f32_e32 v26, 0xbfb8aa3b, v11
	v_exp_f32_e32 v25, v25
	v_exp_f32_e32 v26, v26
	v_mul_f32_e32 v17, 0xbfb8aa3b, v12
	v_mul_f32_e32 v20, 0xbfb8aa3b, v13
	v_add_f32_e32 v21, 1.0, v21
	v_add_f32_e32 v22, 1.0, v22
	v_add_f32_e32 v23, 1.0, v23
	v_add_f32_e32 v24, 1.0, v24
	v_exp_f32_e32 v17, v17
	v_exp_f32_e32 v20, v20
	v_rcp_f32_e32 v21, v21
	v_rcp_f32_e32 v22, v22
	v_rcp_f32_e32 v23, v23
	v_rcp_f32_e32 v24, v24
	v_add_f32_e32 v25, 1.0, v25
	v_add_f32_e32 v26, 1.0, v26
	v_rcp_f32_e32 v25, v25
	v_rcp_f32_e32 v26, v26
	v_add_f32_e32 v17, 1.0, v17
	v_add_f32_e32 v20, 1.0, v20
	v_cvt_pk_bf16_f32 v21, v21, v22
	v_cvt_pk_bf16_f32 v22, v23, v24
	v_lshl_add_u32 v24, v18, 13, v19
	v_rcp_f32_e32 v17, v17
	v_rcp_f32_e32 v20, v20
	v_cvt_pk_bf16_f32 v23, v25, v26
	v_ashrrev_i32_e32 v25, 31, v24
	v_lshlrev_b64 v[24:25], 12, v[24:25]
	v_lshl_add_u64 v[24:25], v[148:149], 0, v[24:25]
	v_add_co_u32_e32 v24, vcc, 0xfffff000, v24
	v_cvt_pk_bf16_f32 v20, v17, v20
	s_nop 0
	v_addc_co_u32_e32 v25, vcc, -1, v25, vcc
	global_store_dwordx4 v[24:25], v[20:23], off offset:-2560 nt

; __device__ __forceinline__ unsigned pk_bf16(float lo, float hi) { const f32x2 v = {lo, hi}; return __builtin_bit_cast(unsigned, __builtin_convertvector(v, b16x2)); }
; __device__ __forceinline__ float sigmoidf_(float x) { return __builtin_amdgcn_rcpf(1.0f + __expf(-x)); }
;     __device__ __forceinline__ void half(int row, int col32, int fq, const f32x4& v0, const f32x4& v1) const {
;     ...
;             } else if (t >= NMETA && t < T) {
;                 u32x4 w; w.x = pk_bf16(sigmoidf_(v0[0]), sigmoidf_(v0[1])); w.y = pk_bf16(sigmoidf_(v0[2]), sigmoidf_(v0[3]));
;                 w.z = pk_bf16(sigmoidf_(v1[0]), sigmoidf_(v1[1])); w.w = pk_bf16(sigmoidf_(v1[2]), sigmoidf_(v1[3]));
;                 *(u32x4*)(gates + (size_t)(b * SEQ + t - NMETA) * 2048 + (col - 3328)) = w;
;             }
.LBB0_738:
	v_cmp_gt_u32_e32 vcc, s40, v19
	s_and_saveexec_b64 s[4:5], vcc
	s_cbranch_execz .LBB0_740
	v_mul_f32_e32 v8, 0xbfb8aa3b, v4
	v_mul_f32_e32 v9, 0xbfb8aa3b, v5
	v_mul_f32_e32 v10, 0xbfb8aa3b, v6
	v_mul_f32_e32 v11, 0xbfb8aa3b, v7
	v_mul_f32_e32 v12, 0xbfb8aa3b, v0
	v_mul_f32_e32 v13, 0xbfb8aa3b, v1
	v_exp_f32_e32 v8, v8
	v_exp_f32_e32 v9, v9
	v_exp_f32_e32 v10, v10
	v_exp_f32_e32 v11, v11
	v_exp_f32_e32 v12, v12
	v_exp_f32_e32 v13, v13
	v_add_f32_e32 v8, 1.0, v8
	v_add_f32_e32 v9, 1.0, v9
	v_add_f32_e32 v10, 1.0, v10
	v_add_f32_e32 v11, 1.0, v11
	v_add_f32_e32 v12, 1.0, v12
	v_add_f32_e32 v13, 1.0, v13
	v_mul_f32_e32 v14, 0xbfb8aa3b, v2
	v_mul_f32_e32 v15, 0xbfb8aa3b, v3
	v_rcp_f32_e32 v8, v8
	v_rcp_f32_e32 v9, v9
	v_rcp_f32_e32 v10, v10
	v_rcp_f32_e32 v11, v11
	v_rcp_f32_e32 v12, v12
	v_exp_f32_e32 v14, v14
	v_exp_f32_e32 v15, v15
	v_rcp_f32_e32 v13, v13
	v_cvt_pk_bf16_f32 v8, v8, v9
	v_add_f32_e32 v14, 1.0, v14
	v_add_f32_e32 v15, 1.0, v15
	v_cvt_pk_bf16_f32 v9, v10, v11
	v_cvt_pk_bf16_f32 v10, v12, v13
	v_lshl_add_u32 v12, v18, 13, v19
	v_rcp_f32_e32 v14, v14
	v_rcp_f32_e32 v15, v15
	v_ashrrev_i32_e32 v13, 31, v12
	v_lshlrev_b64 v[12:13], 12, v[12:13]
	v_lshl_add_u64 v[12:13], v[148:149], 0, v[12:13]
	v_add_co_u32_e32 v12, vcc, 0xfffff000, v12
	v_cvt_pk_bf16_f32 v11, v14, v15
	s_nop 0
	v_addc_co_u32_e32 v13, vcc, -1, v13, vcc
	global_store_dwordx4 v[12:13], v[8:11], off offset:-2304 nt
